# v61 plus P0 transpose early-wait removal (32 loads in flight before the first wait) and first P V fragment reads issued before the softmax
# speedup vs baseline: 1.0064x; 1.0029x over previous
.LBB0_32:
	v_lshl_add_u64 v[6:7], v[2:3], 0, s[8:9]
	v_add_co_u32_e32 v8, vcc, 0x15000, v6
	global_load_dword v5, v[6:7], off
	s_nop 0
	v_addc_co_u32_e32 v9, vcc, 0, v7, vcc
	v_add_co_u32_e32 v24, vcc, 0x2b000, v6
	global_load_dword v10, v[8:9], off offset:2048
	s_nop 0
	v_addc_co_u32_e32 v25, vcc, 0, v7, vcc
	v_add_co_u32_e32 v8, vcc, 0x40000, v6
	s_add_u32 s8, s8, 0x2b0000
	s_nop 0
	v_addc_co_u32_e32 v9, vcc, 0, v7, vcc
	v_add_co_u32_e32 v54, vcc, 0x56000, v6
	global_load_dword v56, v[24:25], off
	global_load_dword v57, v[8:9], off offset:2048
	v_addc_co_u32_e32 v55, vcc, 0, v7, vcc
	v_add_co_u32_e32 v8, vcc, 0x6b000, v6
	s_addc_u32 s9, s9, 0
	s_nop 0
	v_addc_co_u32_e32 v9, vcc, 0, v7, vcc
	v_add_co_u32_e32 v24, vcc, 0x81000, v6
	global_load_dword v58, v[54:55], off
	global_load_dword v59, v[8:9], off offset:2048
	v_addc_co_u32_e32 v25, vcc, 0, v7, vcc
	v_add_co_u32_e32 v8, vcc, 0x96000, v6
	s_cmp_lg_u32 s8, 0x560000
	s_nop 0
	v_addc_co_u32_e32 v9, vcc, 0, v7, vcc
	v_add_co_u32_e32 v54, vcc, 0xac000, v6
	global_load_dword v60, v[24:25], off
	global_load_dword v61, v[8:9], off offset:2048
	v_addc_co_u32_e32 v55, vcc, 0, v7, vcc
	v_add_co_u32_e32 v8, vcc, 0xc1000, v6
	v_addc_co_u32_e32 v9, vcc, 0, v7, vcc
	v_add_co_u32_e32 v24, vcc, 0xd7000, v6
	global_load_dword v62, v[54:55], off
	global_load_dword v63, v[8:9], off offset:2048
	v_addc_co_u32_e32 v25, vcc, 0, v7, vcc
	v_add_co_u32_e32 v8, vcc, 0xec000, v6
	v_addc_co_u32_e32 v9, vcc, 0, v7, vcc
	v_add_co_u32_e32 v54, vcc, 0x102000, v6
	global_load_dword v64, v[24:25], off
	global_load_dword v65, v[8:9], off offset:2048
	v_addc_co_u32_e32 v55, vcc, 0, v7, vcc
	v_add_co_u32_e32 v8, vcc, 0x117000, v6
	s_nop 1
	v_addc_co_u32_e32 v9, vcc, 0, v7, vcc
	v_add_co_u32_e32 v24, vcc, 0x12d000, v6
	global_load_dword v66, v[54:55], off
	global_load_dword v67, v[8:9], off offset:2048
	v_addc_co_u32_e32 v25, vcc, 0, v7, vcc
	v_add_co_u32_e32 v8, vcc, 0x142000, v6
	s_nop 1
	v_addc_co_u32_e32 v9, vcc, 0, v7, vcc
	v_add_co_u32_e32 v54, vcc, 0x158000, v6
	global_load_dword v68, v[24:25], off
	global_load_dword v69, v[8:9], off offset:2048
	v_addc_co_u32_e32 v55, vcc, 0, v7, vcc
	v_add_co_u32_e32 v8, vcc, 0x16d000, v6
	s_nop 1
	v_addc_co_u32_e32 v9, vcc, 0, v7, vcc
	v_add_co_u32_e32 v24, vcc, 0x183000, v6
	global_load_dword v70, v[54:55], off
	global_load_dword v71, v[8:9], off offset:2048
	v_addc_co_u32_e32 v25, vcc, 0, v7, vcc
	v_add_co_u32_e32 v8, vcc, 0x198000, v6
	s_nop 1
	v_addc_co_u32_e32 v9, vcc, 0, v7, vcc
	v_add_co_u32_e32 v54, vcc, 0x1ae000, v6
	global_load_dword v72, v[24:25], off
	global_load_dword v73, v[8:9], off offset:2048
	v_addc_co_u32_e32 v55, vcc, 0, v7, vcc
	v_add_co_u32_e32 v8, vcc, 0x1c3000, v6
	s_nop 1
	v_addc_co_u32_e32 v9, vcc, 0, v7, vcc
	v_add_co_u32_e32 v24, vcc, 0x1d9000, v6
	global_load_dword v74, v[54:55], off
	global_load_dword v75, v[8:9], off offset:2048
	v_addc_co_u32_e32 v25, vcc, 0, v7, vcc
	v_add_co_u32_e32 v8, vcc, 0x1ee000, v6
	s_nop 1
	v_addc_co_u32_e32 v9, vcc, 0, v7, vcc
	v_add_co_u32_e32 v54, vcc, 0x204000, v6
	global_load_dword v76, v[24:25], off
	global_load_dword v77, v[8:9], off offset:2048
	v_addc_co_u32_e32 v55, vcc, 0, v7, vcc
	v_add_co_u32_e32 v8, vcc, 0x219000, v6
	s_nop 1
	v_addc_co_u32_e32 v9, vcc, 0, v7, vcc
	v_add_co_u32_e32 v24, vcc, 0x22f000, v6
	global_load_dword v78, v[54:55], off
	global_load_dword v79, v[8:9], off offset:2048
	v_addc_co_u32_e32 v25, vcc, 0, v7, vcc
	v_add_co_u32_e32 v8, vcc, 0x244000, v6
	s_nop 1
	v_addc_co_u32_e32 v9, vcc, 0, v7, vcc
	v_add_co_u32_e32 v54, vcc, 0x25a000, v6
	global_load_dword v80, v[24:25], off
	global_load_dword v81, v[8:9], off offset:2048
	v_addc_co_u32_e32 v55, vcc, 0, v7, vcc
	v_add_co_u32_e32 v8, vcc, 0x26f000, v6
	s_nop 1
	v_addc_co_u32_e32 v9, vcc, 0, v7, vcc
	v_add_co_u32_e32 v24, vcc, 0x285000, v6
	global_load_dword v54, v[54:55], off
	s_nop 0
	global_load_dword v8, v[8:9], off offset:2048
	v_addc_co_u32_e32 v25, vcc, 0, v7, vcc
	v_add_co_u32_e32 v6, vcc, 0x29a000, v6
	s_nop 1
	v_addc_co_u32_e32 v7, vcc, 0, v7, vcc
	global_load_dword v9, v[24:25], off
	s_nop 0
	global_load_dword v6, v[6:7], off offset:2048
	s_waitcnt vmcnt(30)
	v_cvt_pk_bf16_f32 v5, v5, v10
	s_waitcnt vmcnt(28)
	v_cvt_pk_bf16_f32 v10, v56, v57
	ds_write2_b32 v4, v5, v10 offset1:65
	s_waitcnt vmcnt(26)
	v_cvt_pk_bf16_f32 v5, v58, v59
	s_waitcnt vmcnt(24)
	v_cvt_pk_bf16_f32 v10, v60, v61
	v_add_u32_e32 v7, 0x400, v4
	ds_write2_b32 v4, v5, v10 offset0:130 offset1:195
	s_waitcnt vmcnt(22)
	v_cvt_pk_bf16_f32 v5, v62, v63
	s_waitcnt vmcnt(20)
	v_cvt_pk_bf16_f32 v10, v64, v65
	ds_write2_b32 v7, v5, v10 offset0:4 offset1:69
	s_waitcnt vmcnt(18)
	v_cvt_pk_bf16_f32 v5, v66, v67
	s_waitcnt vmcnt(16)
	v_cvt_pk_bf16_f32 v10, v68, v69
	v_add_u32_e32 v24, 0x800, v4
	ds_write2_b32 v7, v5, v10 offset0:134 offset1:199
	s_waitcnt vmcnt(14)
	v_cvt_pk_bf16_f32 v5, v70, v71
	v_add_u32_e32 v25, 0xc00, v4
	v_add_u32_e32 v4, 0x1040, v4
	s_waitcnt vmcnt(12)
	v_cvt_pk_bf16_f32 v7, v72, v73
	ds_write2_b32 v24, v5, v7 offset0:8 offset1:73
	s_waitcnt vmcnt(10)
	v_cvt_pk_bf16_f32 v5, v74, v75
	s_waitcnt vmcnt(8)
	v_cvt_pk_bf16_f32 v7, v76, v77
	ds_write2_b32 v24, v5, v7 offset0:138 offset1:203
	s_waitcnt vmcnt(6)
	v_cvt_pk_bf16_f32 v5, v78, v79
	s_waitcnt vmcnt(4)
	v_cvt_pk_bf16_f32 v7, v80, v81
	ds_write2_b32 v25, v5, v7 offset0:12 offset1:77
	s_waitcnt vmcnt(2)
	v_cvt_pk_bf16_f32 v5, v54, v8
	s_waitcnt vmcnt(0)
	v_cvt_pk_bf16_f32 v6, v9, v6
	ds_write2_b32 v25, v5, v6 offset0:142 offset1:207
	s_cbranch_scc1 .LBB0_32
	s_add_i32 s4, s0, 0xffffc000
	s_mul_i32 s8, s4, 0xbe83
	s_waitcnt lgkmcnt(0)
	s_lshr_b32 s9, s8, 24
	s_mul_i32 s8, s9, 0xfffffea8
	ds_read2_b32 v[24:25], v27 offset1:8
	ds_read2_b32 v[2:3], v27 offset0:65 offset1:73
	ds_read2_b32 v[54:55], v27 offset0:130 offset1:138
	ds_read2_b32 v[4:5], v27 offset0:195 offset1:203
	s_add_i32 s8, s8, s4
	s_lshl_b32 s8, s8, 6
	s_waitcnt lgkmcnt(2)
	v_mov_b32_e32 v7, v2
	v_or_b32_e32 v2, s8, v26
	v_cmp_lt_i32_e32 vcc, s40, v2
	s_waitcnt lgkmcnt(0)
	v_mov_b32_e32 v9, v4
	v_bitop3_b32 v10, s8, v45, v26 bitop3:0xc8
	v_cndmask_b32_e32 v4, 0, v43, vcc
	v_add_lshl_u32 v2, v4, v2, 1
	v_and_b32_e32 v2, 0xffffff00, v2
	v_cndmask_b32_e32 v4, 0, v44, vcc
	v_or3_b32 v58, v4, v10, v2
	s_lshl_b32 s4, s9, 7
	v_ashrrev_i32_e32 v59, 31, v58
	v_lshl_add_u64 v[56:57], v[12:13], 0, s[4:5]
	v_lshlrev_b64 v[58:59], 13, v[58:59]
	v_mov_b32_e32 v6, v24
	v_mov_b32_e32 v8, v54
	v_lshl_add_u64 v[58:59], v[56:57], 0, v[58:59]
	global_store_dwordx4 v[58:59], v[6:9], off
	v_mov_b32_e32 v2, v25
	v_mov_b32_e32 v4, v55
	v_or_b32_e32 v6, s8, v28
	v_cmp_lt_i32_e32 vcc, s40, v6
	v_bitop3_b32 v8, s8, v46, v28 bitop3:0xc8
	v_bitop3_b32 v10, s8, v47, v29 bitop3:0xc8
	v_cndmask_b32_e32 v7, 0, v43, vcc
	v_add_lshl_u32 v6, v7, v6, 1
	v_and_b32_e32 v6, 0xffffff00, v6
	v_cndmask_b32_e32 v7, 0, v44, vcc
	v_or3_b32 v6, v7, v8, v6
	v_ashrrev_i32_e32 v7, 31, v6
	v_lshlrev_b64 v[6:7], 13, v[6:7]
	v_lshl_add_u64 v[24:25], v[56:57], 0, v[6:7]
	ds_read2_b32 v[54:55], v27 offset0:16 offset1:24
	ds_read2_b32 v[6:7], v27 offset0:81 offset1:89
	ds_read2_b32 v[58:59], v27 offset0:146 offset1:154
	ds_read2_b32 v[8:9], v27 offset0:211 offset1:219
	global_store_dwordx4 v[24:25], v[2:5], off
	s_waitcnt lgkmcnt(2)
	s_nop 0
	v_mov_b32_e32 v3, v6
	v_or_b32_e32 v6, s8, v29
	v_cmp_lt_i32_e32 vcc, s40, v6
	s_waitcnt lgkmcnt(0)
	v_mov_b32_e32 v5, v8
	v_mov_b32_e32 v2, v54
	v_cndmask_b32_e32 v8, 0, v43, vcc
	v_add_lshl_u32 v6, v8, v6, 1
	v_and_b32_e32 v6, 0xffffff00, v6
	v_cndmask_b32_e32 v8, 0, v44, vcc
	v_or3_b32 v24, v8, v10, v6
	v_ashrrev_i32_e32 v25, 31, v24
	v_lshlrev_b64 v[24:25], 13, v[24:25]
	v_mov_b32_e32 v4, v58
	v_lshl_add_u64 v[24:25], v[56:57], 0, v[24:25]
	global_store_dwordx4 v[24:25], v[2:5], off
	v_mov_b32_e32 v6, v55
	v_mov_b32_e32 v8, v59
	v_or_b32_e32 v2, s8, v30
	v_cmp_lt_i32_e32 vcc, s40, v2
	v_bitop3_b32 v4, s8, v48, v30 bitop3:0xc8
	v_bitop3_b32 v10, s8, v49, v31 bitop3:0xc8
	v_cndmask_b32_e32 v3, 0, v43, vcc
	v_add_lshl_u32 v2, v3, v2, 1
	v_and_b32_e32 v2, 0xffffff00, v2
	v_cndmask_b32_e32 v3, 0, v44, vcc
	v_or3_b32 v2, v3, v4, v2
	v_ashrrev_i32_e32 v3, 31, v2
	v_lshlrev_b64 v[2:3], 13, v[2:3]
	v_lshl_add_u64 v[24:25], v[56:57], 0, v[2:3]
	ds_read2_b32 v[54:55], v27 offset0:32 offset1:40
	ds_read2_b32 v[2:3], v27 offset0:97 offset1:105
	ds_read2_b32 v[58:59], v27 offset0:162 offset1:170
	ds_read2_b32 v[4:5], v27 offset0:227 offset1:235
	global_store_dwordx4 v[24:25], v[6:9], off
	s_waitcnt lgkmcnt(2)
	s_nop 0
	v_mov_b32_e32 v7, v2
	v_or_b32_e32 v2, s8, v31
	v_cmp_lt_i32_e32 vcc, s40, v2
	s_waitcnt lgkmcnt(0)
	v_mov_b32_e32 v9, v4
	v_mov_b32_e32 v6, v54
	v_cndmask_b32_e32 v4, 0, v43, vcc
	v_add_lshl_u32 v2, v4, v2, 1
	v_and_b32_e32 v2, 0xffffff00, v2
	v_cndmask_b32_e32 v4, 0, v44, vcc
	v_or3_b32 v24, v4, v10, v2
	v_ashrrev_i32_e32 v25, 31, v24
	v_lshlrev_b64 v[24:25], 13, v[24:25]
	v_mov_b32_e32 v8, v58
	v_lshl_add_u64 v[24:25], v[56:57], 0, v[24:25]
	global_store_dwordx4 v[24:25], v[6:9], off
	v_mov_b32_e32 v2, v55
	v_mov_b32_e32 v4, v59
	v_or_b32_e32 v6, s8, v32
	v_cmp_lt_i32_e32 vcc, s40, v6
	v_bitop3_b32 v8, s8, v50, v32 bitop3:0xc8
	v_bitop3_b32 v10, s8, v51, v33 bitop3:0xc8
	v_cndmask_b32_e32 v7, 0, v43, vcc
	v_add_lshl_u32 v6, v7, v6, 1
	v_and_b32_e32 v6, 0xffffff00, v6
	v_cndmask_b32_e32 v7, 0, v44, vcc
	v_or3_b32 v6, v7, v8, v6
	v_ashrrev_i32_e32 v7, 31, v6
	v_lshlrev_b64 v[6:7], 13, v[6:7]
	v_lshl_add_u64 v[24:25], v[56:57], 0, v[6:7]
	ds_read2_b32 v[54:55], v27 offset0:48 offset1:56
	ds_read2_b32 v[6:7], v27 offset0:113 offset1:121
	ds_read2_b32 v[58:59], v27 offset0:178 offset1:186
	ds_read2_b32 v[8:9], v27 offset0:243 offset1:251
	global_store_dwordx4 v[24:25], v[2:5], off
	s_waitcnt lgkmcnt(2)
	s_nop 0
	v_mov_b32_e32 v3, v6
	v_or_b32_e32 v6, s8, v33
	v_cmp_lt_i32_e32 vcc, s40, v6
	s_waitcnt lgkmcnt(0)
	v_mov_b32_e32 v5, v8
	v_mov_b32_e32 v2, v54
	v_cndmask_b32_e32 v8, 0, v43, vcc
	v_add_lshl_u32 v6, v8, v6, 1
	v_and_b32_e32 v6, 0xffffff00, v6
	v_cndmask_b32_e32 v8, 0, v44, vcc
	v_or3_b32 v24, v8, v10, v6
	v_ashrrev_i32_e32 v25, 31, v24
	v_lshlrev_b64 v[24:25], 13, v[24:25]
	v_mov_b32_e32 v4, v58
	v_lshl_add_u64 v[24:25], v[56:57], 0, v[24:25]
	global_store_dwordx4 v[24:25], v[2:5], off
	v_mov_b32_e32 v6, v55
	v_mov_b32_e32 v8, v59
	v_or_b32_e32 v2, s8, v34
	v_cmp_lt_i32_e32 vcc, s40, v2
	v_bitop3_b32 v4, s8, v52, v34 bitop3:0xc8
	s_mov_b64 s[8:9], 0
	v_cndmask_b32_e32 v3, 0, v43, vcc
	v_add_lshl_u32 v2, v3, v2, 1
	v_and_b32_e32 v2, 0xffffff00, v2
	v_cndmask_b32_e32 v3, 0, v44, vcc
	v_or3_b32 v2, v3, v4, v2
	v_ashrrev_i32_e32 v3, 31, v2
	v_lshlrev_b64 v[2:3], 13, v[2:3]
	v_lshl_add_u64 v[2:3], v[56:57], 0, v[2:3]
	global_store_dwordx4 v[2:3], v[6:9], off
	s_waitcnt lgkmcnt(0)

.LBB0_36:
	v_lshl_add_u64 v[6:7], v[2:3], 0, s[8:9]
	v_add_co_u32_e32 v8, vcc, 0x4000, v6
	global_load_dword v5, v[6:7], off
	s_nop 0
	v_addc_co_u32_e32 v9, vcc, 0, v7, vcc
	v_add_co_u32_e32 v24, vcc, 0x8000, v6
	global_load_dword v10, v[8:9], off
	s_nop 0
	v_addc_co_u32_e32 v25, vcc, 0, v7, vcc
	v_add_co_u32_e32 v8, vcc, s1, v6
	s_add_u32 s8, s8, 0x80000
	s_nop 0
	v_addc_co_u32_e32 v9, vcc, 0, v7, vcc
	v_add_co_u32_e32 v54, vcc, 0x10000, v6
	global_load_dword v56, v[24:25], off
	global_load_dword v57, v[8:9], off
	v_addc_co_u32_e32 v55, vcc, 0, v7, vcc
	v_add_co_u32_e32 v8, vcc, 0x14000, v6
	s_addc_u32 s9, s9, 0
	s_nop 0
	v_addc_co_u32_e32 v9, vcc, 0, v7, vcc
	v_add_co_u32_e32 v24, vcc, 0x18000, v6
	global_load_dword v58, v[54:55], off
	global_load_dword v59, v[8:9], off
	v_addc_co_u32_e32 v25, vcc, 0, v7, vcc
	v_add_co_u32_e32 v8, vcc, 0x1c000, v6
	s_cmp_lg_u32 s8, 0x100000
	s_nop 0
	v_addc_co_u32_e32 v9, vcc, 0, v7, vcc
	v_add_co_u32_e32 v54, vcc, 0x20000, v6
	global_load_dword v60, v[24:25], off
	global_load_dword v61, v[8:9], off
	v_addc_co_u32_e32 v55, vcc, 0, v7, vcc
	v_add_co_u32_e32 v8, vcc, 0x24000, v6
	v_addc_co_u32_e32 v9, vcc, 0, v7, vcc
	v_add_co_u32_e32 v24, vcc, 0x28000, v6
	global_load_dword v62, v[54:55], off
	global_load_dword v63, v[8:9], off
	v_addc_co_u32_e32 v25, vcc, 0, v7, vcc
	v_add_co_u32_e32 v8, vcc, 0x2c000, v6
	v_addc_co_u32_e32 v9, vcc, 0, v7, vcc
	v_add_co_u32_e32 v54, vcc, 0x30000, v6
	global_load_dword v64, v[24:25], off
	global_load_dword v65, v[8:9], off
	v_addc_co_u32_e32 v55, vcc, 0, v7, vcc
	v_add_co_u32_e32 v8, vcc, 0x34000, v6
	s_nop 1
	v_addc_co_u32_e32 v9, vcc, 0, v7, vcc
	v_add_co_u32_e32 v24, vcc, 0x38000, v6
	global_load_dword v66, v[54:55], off
	global_load_dword v67, v[8:9], off
	v_addc_co_u32_e32 v25, vcc, 0, v7, vcc
	v_add_co_u32_e32 v8, vcc, 0x3c000, v6
	s_nop 1
	v_addc_co_u32_e32 v9, vcc, 0, v7, vcc
	v_add_co_u32_e32 v54, vcc, s39, v6
	global_load_dword v68, v[24:25], off
	global_load_dword v69, v[8:9], off
	v_addc_co_u32_e32 v55, vcc, 0, v7, vcc
	v_add_co_u32_e32 v8, vcc, 0x44000, v6
	s_nop 1
	v_addc_co_u32_e32 v9, vcc, 0, v7, vcc
	v_add_co_u32_e32 v24, vcc, 0x48000, v6
	global_load_dword v70, v[54:55], off
	global_load_dword v71, v[8:9], off
	v_addc_co_u32_e32 v25, vcc, 0, v7, vcc
	v_add_co_u32_e32 v8, vcc, 0x4c000, v6
	s_nop 1
	v_addc_co_u32_e32 v9, vcc, 0, v7, vcc
	v_add_co_u32_e32 v54, vcc, 0x50000, v6
	global_load_dword v72, v[24:25], off
	global_load_dword v73, v[8:9], off
	v_addc_co_u32_e32 v55, vcc, 0, v7, vcc
	v_add_co_u32_e32 v8, vcc, 0x54000, v6
	s_nop 1
	v_addc_co_u32_e32 v9, vcc, 0, v7, vcc
	v_add_co_u32_e32 v24, vcc, 0x58000, v6
	global_load_dword v74, v[54:55], off
	global_load_dword v75, v[8:9], off
	v_addc_co_u32_e32 v25, vcc, 0, v7, vcc
	v_add_co_u32_e32 v8, vcc, 0x5c000, v6
	s_nop 1
	v_addc_co_u32_e32 v9, vcc, 0, v7, vcc
	v_add_co_u32_e32 v54, vcc, 0x60000, v6
	global_load_dword v76, v[24:25], off
	global_load_dword v77, v[8:9], off
	v_addc_co_u32_e32 v55, vcc, 0, v7, vcc
	v_add_co_u32_e32 v8, vcc, 0x64000, v6
	s_nop 1
	v_addc_co_u32_e32 v9, vcc, 0, v7, vcc
	v_add_co_u32_e32 v24, vcc, 0x68000, v6
	global_load_dword v78, v[54:55], off
	global_load_dword v79, v[8:9], off
	v_addc_co_u32_e32 v25, vcc, 0, v7, vcc
	v_add_co_u32_e32 v8, vcc, 0x6c000, v6
	s_nop 1
	v_addc_co_u32_e32 v9, vcc, 0, v7, vcc
	v_add_co_u32_e32 v54, vcc, 0x70000, v6
	global_load_dword v80, v[24:25], off
	global_load_dword v81, v[8:9], off
	v_addc_co_u32_e32 v55, vcc, 0, v7, vcc
	v_add_co_u32_e32 v8, vcc, 0x74000, v6
	s_nop 1
	v_addc_co_u32_e32 v9, vcc, 0, v7, vcc
	v_add_co_u32_e32 v24, vcc, 0x78000, v6
	global_load_dword v54, v[54:55], off
	s_nop 0
	global_load_dword v8, v[8:9], off
	v_addc_co_u32_e32 v25, vcc, 0, v7, vcc
	v_add_co_u32_e32 v6, vcc, 0x7c000, v6
	s_nop 1
	v_addc_co_u32_e32 v7, vcc, 0, v7, vcc
	global_load_dword v9, v[24:25], off
	s_nop 0
	global_load_dword v6, v[6:7], off
	s_waitcnt vmcnt(30)
	v_cvt_pk_bf16_f32 v5, v5, v10
	s_waitcnt vmcnt(28)
	v_cvt_pk_bf16_f32 v10, v56, v57
	ds_write2_b32 v4, v5, v10 offset1:65
	s_waitcnt vmcnt(26)
	v_cvt_pk_bf16_f32 v5, v58, v59
	s_waitcnt vmcnt(24)
	v_cvt_pk_bf16_f32 v10, v60, v61
	v_add_u32_e32 v7, 0x400, v4
	ds_write2_b32 v4, v5, v10 offset0:130 offset1:195
	s_waitcnt vmcnt(22)
	v_cvt_pk_bf16_f32 v5, v62, v63
	s_waitcnt vmcnt(20)
	v_cvt_pk_bf16_f32 v10, v64, v65
	ds_write2_b32 v7, v5, v10 offset0:4 offset1:69
	s_waitcnt vmcnt(18)
	v_cvt_pk_bf16_f32 v5, v66, v67
	s_waitcnt vmcnt(16)
	v_cvt_pk_bf16_f32 v10, v68, v69
	v_add_u32_e32 v24, 0x800, v4
	ds_write2_b32 v7, v5, v10 offset0:134 offset1:199
	s_waitcnt vmcnt(14)
	v_cvt_pk_bf16_f32 v5, v70, v71
	v_add_u32_e32 v25, 0xc00, v4
	v_add_u32_e32 v4, 0x1040, v4
	s_waitcnt vmcnt(12)
	v_cvt_pk_bf16_f32 v7, v72, v73
	ds_write2_b32 v24, v5, v7 offset0:8 offset1:73
	s_waitcnt vmcnt(10)
	v_cvt_pk_bf16_f32 v5, v74, v75
	s_waitcnt vmcnt(8)
	v_cvt_pk_bf16_f32 v7, v76, v77
	ds_write2_b32 v24, v5, v7 offset0:138 offset1:203
	s_waitcnt vmcnt(6)
	v_cvt_pk_bf16_f32 v5, v78, v79
	s_waitcnt vmcnt(4)
	v_cvt_pk_bf16_f32 v7, v80, v81
	ds_write2_b32 v25, v5, v7 offset0:12 offset1:77
	s_waitcnt vmcnt(2)
	v_cvt_pk_bf16_f32 v5, v54, v8
	s_waitcnt vmcnt(0)
	v_cvt_pk_bf16_f32 v6, v9, v6
	ds_write2_b32 v25, v5, v6 offset0:142 offset1:207
	s_cbranch_scc1 .LBB0_36
	s_waitcnt lgkmcnt(0)
	ds_read2_b32 v[24:25], v27 offset1:8
	ds_read2_b32 v[2:3], v27 offset0:65 offset1:73
	ds_read2_b32 v[54:55], v27 offset0:130 offset1:138
	ds_read2_b32 v[4:5], v27 offset0:195 offset1:203
	s_lshl_b32 s8, s0, 6
	s_and_b32 s4, s0, 0xfc0
	s_and_b32 s8, s8, 0xfc0
	s_lshl_b32 s4, s4, 1
	s_waitcnt lgkmcnt(2)
	v_mov_b32_e32 v7, v2
	v_or_b32_e32 v2, s8, v26
	v_lshl_add_u64 v[56:57], v[14:15], 0, s[4:5]
	v_lshlrev_b32_e32 v10, 13, v2
	v_mov_b32_e32 v6, v24
	s_waitcnt lgkmcnt(1)
	v_mov_b32_e32 v8, v54
	s_waitcnt lgkmcnt(0)
	v_mov_b32_e32 v9, v4
	v_lshl_add_u64 v[58:59], v[56:57], 0, v[10:11]
	global_store_dwordx4 v[58:59], v[6:9], off
	v_mov_b32_e32 v4, v55
	v_mov_b32_e32 v2, v25
	v_or_b32_e32 v6, s8, v28
	v_lshlrev_b32_e32 v10, 13, v6
	ds_read2_b32 v[54:55], v27 offset0:16 offset1:24
	ds_read2_b32 v[6:7], v27 offset0:81 offset1:89
	ds_read2_b32 v[58:59], v27 offset0:146 offset1:154
	ds_read2_b32 v[8:9], v27 offset0:211 offset1:219
	v_lshl_add_u64 v[24:25], v[56:57], 0, v[10:11]
	global_store_dwordx4 v[24:25], v[2:5], off
	s_waitcnt lgkmcnt(2)
	s_nop 0
	v_mov_b32_e32 v3, v6
	v_or_b32_e32 v6, s8, v29
	v_lshlrev_b32_e32 v10, 13, v6
	v_mov_b32_e32 v2, v54
	s_waitcnt lgkmcnt(1)
	v_mov_b32_e32 v4, v58
	s_waitcnt lgkmcnt(0)
	v_mov_b32_e32 v5, v8
	v_lshl_add_u64 v[24:25], v[56:57], 0, v[10:11]
	global_store_dwordx4 v[24:25], v[2:5], off
	v_mov_b32_e32 v6, v55
	v_mov_b32_e32 v8, v59
	v_or_b32_e32 v2, s8, v30
	v_lshlrev_b32_e32 v10, 13, v2
	ds_read2_b32 v[54:55], v27 offset0:32 offset1:40
	ds_read2_b32 v[2:3], v27 offset0:97 offset1:105
	ds_read2_b32 v[58:59], v27 offset0:162 offset1:170
	ds_read2_b32 v[4:5], v27 offset0:227 offset1:235
	v_lshl_add_u64 v[24:25], v[56:57], 0, v[10:11]
	global_store_dwordx4 v[24:25], v[6:9], off
	s_waitcnt lgkmcnt(2)
	s_nop 0
	v_mov_b32_e32 v7, v2
	v_or_b32_e32 v2, s8, v31
	v_lshlrev_b32_e32 v10, 13, v2
	v_mov_b32_e32 v6, v54
	s_waitcnt lgkmcnt(1)
	v_mov_b32_e32 v8, v58
	s_waitcnt lgkmcnt(0)
	v_mov_b32_e32 v9, v4
	v_lshl_add_u64 v[24:25], v[56:57], 0, v[10:11]
	global_store_dwordx4 v[24:25], v[6:9], off
	v_mov_b32_e32 v2, v55
	v_mov_b32_e32 v4, v59
	v_or_b32_e32 v6, s8, v32
	v_lshlrev_b32_e32 v10, 13, v6
	ds_read2_b32 v[54:55], v27 offset0:48 offset1:56
	ds_read2_b32 v[6:7], v27 offset0:113 offset1:121
	ds_read2_b32 v[58:59], v27 offset0:178 offset1:186
	ds_read2_b32 v[8:9], v27 offset0:243 offset1:251
	v_lshl_add_u64 v[24:25], v[56:57], 0, v[10:11]
	global_store_dwordx4 v[24:25], v[2:5], off
	s_waitcnt lgkmcnt(2)
	s_nop 0
	v_mov_b32_e32 v3, v6
	v_or_b32_e32 v6, s8, v33
	v_lshlrev_b32_e32 v10, 13, v6
	v_mov_b32_e32 v2, v54
	s_waitcnt lgkmcnt(1)
	v_mov_b32_e32 v4, v58
	s_waitcnt lgkmcnt(0)
	v_mov_b32_e32 v5, v8
	v_lshl_add_u64 v[24:25], v[56:57], 0, v[10:11]
	global_store_dwordx4 v[24:25], v[2:5], off
	v_mov_b32_e32 v6, v55
	v_mov_b32_e32 v8, v59
	v_or_b32_e32 v2, s8, v34
	v_lshlrev_b32_e32 v10, 13, v2
	v_lshl_add_u64 v[2:3], v[56:57], 0, v[10:11]
	global_store_dwordx4 v[2:3], v[6:9], off
	s_waitcnt lgkmcnt(0)

.LBB0_41:
	v_lshl_add_u64 v[6:7], v[2:3], 0, s[24:25]
	v_add_co_u32_e32 v8, vcc, 0xc000, v6
	global_load_dword v5, v[6:7], off
	s_nop 0
	v_addc_co_u32_e32 v9, vcc, 0, v7, vcc
	v_add_co_u32_e32 v24, vcc, 0x18000, v6
	global_load_dword v10, v[8:9], off
	s_nop 0
	v_addc_co_u32_e32 v25, vcc, 0, v7, vcc
	v_add_co_u32_e32 v8, vcc, 0x24000, v6
	s_add_u32 s24, s24, 0x180000
	s_nop 0
	v_addc_co_u32_e32 v9, vcc, 0, v7, vcc
	v_add_co_u32_e32 v54, vcc, 0x30000, v6
	global_load_dword v56, v[24:25], off
	global_load_dword v57, v[8:9], off
	v_addc_co_u32_e32 v55, vcc, 0, v7, vcc
	v_add_co_u32_e32 v8, vcc, 0x3c000, v6
	s_addc_u32 s25, s25, 0
	s_nop 0
	v_addc_co_u32_e32 v9, vcc, 0, v7, vcc
	v_add_co_u32_e32 v24, vcc, 0x48000, v6
	global_load_dword v58, v[54:55], off
	global_load_dword v59, v[8:9], off
	v_addc_co_u32_e32 v25, vcc, 0, v7, vcc
	v_add_co_u32_e32 v8, vcc, 0x54000, v6
	s_cmp_eq_u32 s24, 0x300000
	s_nop 0
	v_addc_co_u32_e32 v9, vcc, 0, v7, vcc
	v_add_co_u32_e32 v54, vcc, 0x60000, v6
	global_load_dword v60, v[24:25], off
	global_load_dword v61, v[8:9], off
	v_addc_co_u32_e32 v55, vcc, 0, v7, vcc
	v_add_co_u32_e32 v8, vcc, 0x6c000, v6
	v_addc_co_u32_e32 v9, vcc, 0, v7, vcc
	v_add_co_u32_e32 v24, vcc, 0x78000, v6
	global_load_dword v62, v[54:55], off
	global_load_dword v63, v[8:9], off
	v_addc_co_u32_e32 v25, vcc, 0, v7, vcc
	v_add_co_u32_e32 v8, vcc, 0x84000, v6
	v_addc_co_u32_e32 v9, vcc, 0, v7, vcc
	v_add_co_u32_e32 v54, vcc, 0x90000, v6
	global_load_dword v64, v[24:25], off
	global_load_dword v65, v[8:9], off
	v_addc_co_u32_e32 v55, vcc, 0, v7, vcc
	v_add_co_u32_e32 v8, vcc, 0x9c000, v6
	s_nop 1
	v_addc_co_u32_e32 v9, vcc, 0, v7, vcc
	v_add_co_u32_e32 v24, vcc, 0xa8000, v6
	global_load_dword v66, v[54:55], off
	global_load_dword v67, v[8:9], off
	v_addc_co_u32_e32 v25, vcc, 0, v7, vcc
	v_add_co_u32_e32 v8, vcc, 0xb4000, v6
	s_nop 1
	v_addc_co_u32_e32 v9, vcc, 0, v7, vcc
	v_add_co_u32_e32 v54, vcc, 0xc0000, v6
	global_load_dword v68, v[24:25], off
	global_load_dword v69, v[8:9], off
	v_addc_co_u32_e32 v55, vcc, 0, v7, vcc
	v_add_co_u32_e32 v8, vcc, 0xcc000, v6
	s_nop 1
	v_addc_co_u32_e32 v9, vcc, 0, v7, vcc
	v_add_co_u32_e32 v24, vcc, 0xd8000, v6
	global_load_dword v70, v[54:55], off
	global_load_dword v71, v[8:9], off
	v_addc_co_u32_e32 v25, vcc, 0, v7, vcc
	v_add_co_u32_e32 v8, vcc, 0xe4000, v6
	s_nop 1
	v_addc_co_u32_e32 v9, vcc, 0, v7, vcc
	v_add_co_u32_e32 v54, vcc, 0xf0000, v6
	global_load_dword v72, v[24:25], off
	global_load_dword v73, v[8:9], off
	v_addc_co_u32_e32 v55, vcc, 0, v7, vcc
	v_add_co_u32_e32 v8, vcc, 0xfc000, v6
	s_nop 1
	v_addc_co_u32_e32 v9, vcc, 0, v7, vcc
	v_add_co_u32_e32 v24, vcc, 0x108000, v6
	global_load_dword v74, v[54:55], off
	global_load_dword v75, v[8:9], off
	v_addc_co_u32_e32 v25, vcc, 0, v7, vcc
	v_add_co_u32_e32 v8, vcc, 0x114000, v6
	s_nop 1
	v_addc_co_u32_e32 v9, vcc, 0, v7, vcc
	v_add_co_u32_e32 v54, vcc, 0x120000, v6
	global_load_dword v76, v[24:25], off
	global_load_dword v77, v[8:9], off
	v_addc_co_u32_e32 v55, vcc, 0, v7, vcc
	v_add_co_u32_e32 v8, vcc, 0x12c000, v6
	s_nop 1
	v_addc_co_u32_e32 v9, vcc, 0, v7, vcc
	v_add_co_u32_e32 v24, vcc, 0x138000, v6
	global_load_dword v78, v[54:55], off
	global_load_dword v79, v[8:9], off
	v_addc_co_u32_e32 v25, vcc, 0, v7, vcc
	v_add_co_u32_e32 v8, vcc, 0x144000, v6
	s_nop 1
	v_addc_co_u32_e32 v9, vcc, 0, v7, vcc
	v_add_co_u32_e32 v54, vcc, 0x150000, v6
	global_load_dword v80, v[24:25], off
	global_load_dword v81, v[8:9], off
	v_addc_co_u32_e32 v55, vcc, 0, v7, vcc
	v_add_co_u32_e32 v8, vcc, 0x15c000, v6
	s_nop 1
	v_addc_co_u32_e32 v9, vcc, 0, v7, vcc
	v_add_co_u32_e32 v24, vcc, 0x168000, v6
	global_load_dword v54, v[54:55], off
	s_nop 0
	global_load_dword v8, v[8:9], off
	v_addc_co_u32_e32 v25, vcc, 0, v7, vcc
	v_add_co_u32_e32 v6, vcc, 0x174000, v6
	s_nop 1
	v_addc_co_u32_e32 v7, vcc, 0, v7, vcc
	global_load_dword v9, v[24:25], off
	s_nop 0
	global_load_dword v6, v[6:7], off
	s_waitcnt vmcnt(30)
	v_cvt_pk_bf16_f32 v5, v5, v10
	s_waitcnt vmcnt(28)
	v_cvt_pk_bf16_f32 v10, v56, v57
	ds_write2_b32 v4, v5, v10 offset1:65
	s_waitcnt vmcnt(26)
	v_cvt_pk_bf16_f32 v5, v58, v59
	s_waitcnt vmcnt(24)
	v_cvt_pk_bf16_f32 v10, v60, v61
	v_add_u32_e32 v7, 0x400, v4
	ds_write2_b32 v4, v5, v10 offset0:130 offset1:195
	s_waitcnt vmcnt(22)
	v_cvt_pk_bf16_f32 v5, v62, v63
	s_waitcnt vmcnt(20)
	v_cvt_pk_bf16_f32 v10, v64, v65
	ds_write2_b32 v7, v5, v10 offset0:4 offset1:69
	s_waitcnt vmcnt(18)
	v_cvt_pk_bf16_f32 v5, v66, v67
	s_waitcnt vmcnt(16)
	v_cvt_pk_bf16_f32 v10, v68, v69
	v_add_u32_e32 v24, 0x800, v4
	ds_write2_b32 v7, v5, v10 offset0:134 offset1:199
	s_waitcnt vmcnt(14)
	v_cvt_pk_bf16_f32 v5, v70, v71
	v_add_u32_e32 v25, 0xc00, v4
	v_add_u32_e32 v4, 0x1040, v4
	s_waitcnt vmcnt(12)
	v_cvt_pk_bf16_f32 v7, v72, v73
	ds_write2_b32 v24, v5, v7 offset0:8 offset1:73
	s_waitcnt vmcnt(10)
	v_cvt_pk_bf16_f32 v5, v74, v75
	s_waitcnt vmcnt(8)
	v_cvt_pk_bf16_f32 v7, v76, v77
	ds_write2_b32 v24, v5, v7 offset0:138 offset1:203
	s_waitcnt vmcnt(6)
	v_cvt_pk_bf16_f32 v5, v78, v79
	s_waitcnt vmcnt(4)
	v_cvt_pk_bf16_f32 v7, v80, v81
	ds_write2_b32 v25, v5, v7 offset0:12 offset1:77
	s_waitcnt vmcnt(2)
	v_cvt_pk_bf16_f32 v5, v54, v8
	s_waitcnt vmcnt(0)
	v_cvt_pk_bf16_f32 v6, v9, v6
	ds_write2_b32 v25, v5, v6 offset0:142 offset1:207
	s_cbranch_scc0 .LBB0_41
	s_waitcnt lgkmcnt(0)
	s_mulk_i32 s4, 0xff40
	ds_read2_b32 v[2:3], v27 offset1:65
	ds_read2_b32 v[4:5], v27 offset0:130 offset1:195
	s_add_i32 s12, s4, s0
	s_lshl_b32 s4, s12, 6
	s_lshl_b32 s12, s12, 2
	v_or_b32_e32 v7, s4, v26
	s_and_b32 s43, s12, 4
	v_cmp_gt_i32_e32 vcc, s41, v7
	s_and_saveexec_b64 s[12:13], vcc
	s_xor_b64 s[24:25], exec, s[12:13]
	v_and_b32_e32 v6, 0xffffff83, v7
	v_or3_b32 v6, v6, v35, s43
	v_cmp_lt_i32_e32 vcc, s42, v7
	s_nop 1
	v_cndmask_b32_e32 v6, v6, v7, vcc
	s_andn2_saveexec_b64 s[24:25], s[24:25]
	s_cbranch_execz .LBB0_46
	s_cmpk_gt_u32 s4, 0x27ff
	s_cselect_b32 s12, 0xfffff800, 0
	s_cselect_b32 s13, 0x80, 0
	s_add_i32 s12, s4, s12
	s_lshl_b32 s12, s12, 1
	s_addk_i32 s12, 0xc000
	s_and_b32 s12, s12, 0x7fffff00
	s_or_b32 s12, s12, s13
	s_addk_i32 s12, 0x2000
	v_and_b32_e32 v6, 0x47, v7
	v_or_b32_e32 v6, s12, v6

.LBB0_349:
	v_lshl_add_u32 v239, s79, 15, v226
	ds_read_b64_tr_b16 v[240:241], v239 offset:0
	ds_read_b64_tr_b16 v[242:243], v239 offset:0x800
	ds_read_b64_tr_b16 v[244:245], v239 offset:0x1000
	ds_read_b64_tr_b16 v[246:247], v239 offset:0x1800
	ds_read_b64_tr_b16 v[248:249], v239 offset:0x2000
	ds_read_b64_tr_b16 v[250:251], v239 offset:0x2800
	ds_read_b64_tr_b16 v[252:253], v239 offset:0x3000
	ds_read_b64_tr_b16 v[254:255], v239 offset:0x3800
	s_add_i32 s12, s6, -1
	s_cmp_le_i32 s12, s74
	s_cbranch_scc1 .LBB0_351
	v_add_u32_e32 v2, 27, v227
	v_cmp_lt_i32_e32 vcc, -1, v2
	s_nop 1
	v_cndmask_b32_e32 v162, v220, v162, vcc
	v_cmp_lt_i32_e32 vcc, 31, v2
	v_add_u32_e32 v2, 26, v227
	s_nop 0
	v_cndmask_b32_e32 v146, v220, v146, vcc
	v_cmp_lt_i32_e32 vcc, -1, v2
	s_nop 1
	v_cndmask_b32_e32 v163, v220, v163, vcc
	v_cmp_lt_i32_e32 vcc, 31, v2
	v_add_u32_e32 v2, 25, v227
	s_nop 0
	v_cndmask_b32_e32 v147, v220, v147, vcc
	v_cmp_lt_i32_e32 vcc, -1, v2
	s_nop 1
	v_cndmask_b32_e32 v164, v220, v164, vcc
	v_cmp_lt_i32_e32 vcc, 31, v2
	v_add_u32_e32 v2, 24, v227
	s_nop 0
	v_cndmask_b32_e32 v148, v220, v148, vcc
	v_cmp_lt_i32_e32 vcc, -1, v2
	s_nop 1
	v_cndmask_b32_e32 v165, v220, v165, vcc
	v_cmp_lt_i32_e32 vcc, 31, v2
	v_add_u32_e32 v2, 19, v227
	s_nop 0
	v_cndmask_b32_e32 v149, v220, v149, vcc
	v_cmp_lt_i32_e32 vcc, -1, v2
	s_nop 1
	v_cndmask_b32_e32 v166, v220, v166, vcc
	v_cmp_lt_i32_e32 vcc, 31, v2
	v_add_u32_e32 v2, 18, v227
	s_nop 0
	v_cndmask_b32_e32 v150, v220, v150, vcc
	v_cmp_lt_i32_e32 vcc, -1, v2
	s_nop 1
	v_cndmask_b32_e32 v167, v220, v167, vcc
	v_cmp_lt_i32_e32 vcc, 31, v2
	v_add_u32_e32 v2, 17, v227
	s_nop 0
	v_cndmask_b32_e32 v151, v220, v151, vcc
	v_cmp_lt_i32_e32 vcc, -1, v2
	s_nop 1
	v_cndmask_b32_e32 v168, v220, v168, vcc
	v_cmp_lt_i32_e32 vcc, 31, v2
	v_add_u32_e32 v2, 16, v227
	s_nop 0
	v_cndmask_b32_e32 v152, v220, v152, vcc
	v_cmp_lt_i32_e32 vcc, -1, v2
	s_nop 1
	v_cndmask_b32_e32 v169, v220, v169, vcc
	v_cmp_lt_i32_e32 vcc, 31, v2
	v_add_u32_e32 v2, 11, v227
	s_nop 0
	v_cndmask_b32_e32 v153, v220, v153, vcc
	v_cmp_lt_i32_e32 vcc, -1, v2
	s_nop 1
	v_cndmask_b32_e32 v170, v220, v170, vcc
	v_cmp_lt_i32_e32 vcc, 31, v2
	v_add_u32_e32 v2, 10, v227
	s_nop 0
	v_cndmask_b32_e32 v154, v220, v154, vcc
	v_cmp_lt_i32_e32 vcc, -1, v2
	s_nop 1
	v_cndmask_b32_e32 v171, v220, v171, vcc
	v_cmp_lt_i32_e32 vcc, 31, v2
	v_add_u32_e32 v2, 9, v227
	s_nop 0
	v_cndmask_b32_e32 v155, v220, v155, vcc
	v_cmp_lt_i32_e32 vcc, -1, v2
	s_nop 1
	v_cndmask_b32_e32 v172, v220, v172, vcc
	v_cmp_lt_i32_e32 vcc, 31, v2
	v_add_u32_e32 v2, 8, v227
	s_nop 0
	v_cndmask_b32_e32 v156, v220, v156, vcc
	v_cmp_lt_i32_e32 vcc, -1, v2
	s_nop 1
	v_cndmask_b32_e32 v173, v220, v173, vcc
	v_cmp_lt_i32_e32 vcc, 31, v2
	v_add_u32_e32 v2, 3, v227
	s_nop 0
	v_cndmask_b32_e32 v157, v220, v157, vcc
	v_cmp_lt_i32_e32 vcc, -1, v2
	s_nop 1
	v_cndmask_b32_e32 v174, v220, v174, vcc
	v_cmp_lt_i32_e32 vcc, 31, v2
	v_add_u32_e32 v2, 2, v227
	s_nop 0
	v_cndmask_b32_e32 v158, v220, v158, vcc
	v_cmp_lt_i32_e32 vcc, -1, v2
	s_nop 1
	v_cndmask_b32_e32 v175, v220, v175, vcc
	v_cmp_lt_i32_e32 vcc, 31, v2
	v_add_u32_e32 v2, 1, v227
	s_nop 0
	v_cndmask_b32_e32 v159, v220, v159, vcc
	v_cmp_lt_i32_e32 vcc, -1, v2
	s_nop 1
	v_cndmask_b32_e32 v176, v220, v176, vcc
	v_cmp_lt_i32_e32 vcc, 31, v2
	s_nop 1
	v_cndmask_b32_e32 v160, v220, v160, vcc
	v_cmp_lt_i32_e32 vcc, -1, v227
	s_nop 1
	v_cndmask_b32_e32 v177, v220, v177, vcc
	v_cmp_lt_i32_e32 vcc, 31, v227
	s_nop 1
	v_cndmask_b32_e32 v161, v220, v161, vcc

.LBB0_354:
	v_add_f32_e32 v16, v16, v17
	v_fmac_f32_e32 v16, v229, v2
	v_lshl_add_u32 v2, s79, 15, v226
	ds_read_b64_tr_b16 v[166:167], v2 offset:0x200
	ds_read_b64_tr_b16 v[168:169], v2 offset:0xa00
	ds_read_b64_tr_b16 v[170:171], v2 offset:0x1200
	ds_read_b64_tr_b16 v[172:173], v2 offset:0x1a00
	ds_read_b64_tr_b16 v[174:175], v2 offset:0x2200
	ds_read_b64_tr_b16 v[176:177], v2 offset:0x2a00
	ds_read_b64_tr_b16 v[230:231], v2 offset:0x3200
	ds_read_b64_tr_b16 v[232:233], v2 offset:0x3a00
	s_waitcnt lgkmcnt(8)
	s_nop 0
	v_mfma_f32_32x32x16_bf16 v[130:145], v[240:243], v[4:7], v[130:145]
	v_mfma_f32_32x32x16_bf16 v[130:145], v[244:247], v[8:11], v[130:145]
	v_mfma_f32_32x32x16_bf16 v[130:145], v[248:251], v[146:149], v[130:145]
	v_mfma_f32_32x32x16_bf16 v[130:145], v[252:255], v[12:15], v[130:145]
	ds_read_b64_tr_b16 v[150:151], v2 offset:0x400
	ds_read_b64_tr_b16 v[152:153], v2 offset:0xc00
	ds_read_b64_tr_b16 v[154:155], v2 offset:0x1400
	ds_read_b64_tr_b16 v[156:157], v2 offset:0x1c00
	ds_read_b64_tr_b16 v[158:159], v2 offset:0x2400
	ds_read_b64_tr_b16 v[160:161], v2 offset:0x2c00
	ds_read_b64_tr_b16 v[162:163], v2 offset:0x3400
	ds_read_b64_tr_b16 v[164:165], v2 offset:0x3c00
	s_waitcnt lgkmcnt(8)
	v_mfma_f32_32x32x16_bf16 v[114:129], v[166:169], v[4:7], v[114:129]
	v_mfma_f32_32x32x16_bf16 v[114:129], v[170:173], v[8:11], v[114:129]
	v_mfma_f32_32x32x16_bf16 v[114:129], v[174:177], v[146:149], v[114:129]
	v_mfma_f32_32x32x16_bf16 v[114:129], v[230:233], v[12:15], v[114:129]
	ds_read_b64_tr_b16 v[166:167], v2 offset:0x600
	ds_read_b64_tr_b16 v[168:169], v2 offset:0xe00
	ds_read_b64_tr_b16 v[170:171], v2 offset:0x1600
	ds_read_b64_tr_b16 v[172:173], v2 offset:0x1e00
	ds_read_b64_tr_b16 v[174:175], v2 offset:0x2600
	ds_read_b64_tr_b16 v[176:177], v2 offset:0x2e00
	ds_read_b64_tr_b16 v[230:231], v2 offset:0x3600
	ds_read_b64_tr_b16 v[232:233], v2 offset:0x3e00
	s_waitcnt lgkmcnt(8)
	v_mfma_f32_32x32x16_bf16 v[98:113], v[150:153], v[4:7], v[98:113]
	v_mfma_f32_32x32x16_bf16 v[98:113], v[154:157], v[8:11], v[98:113]
	v_mfma_f32_32x32x16_bf16 v[98:113], v[158:161], v[146:149], v[98:113]
	v_mfma_f32_32x32x16_bf16 v[98:113], v[162:165], v[12:15], v[98:113]
	s_waitcnt lgkmcnt(0)
	v_mfma_f32_32x32x16_bf16 v[82:97], v[166:169], v[4:7], v[82:97]
	v_add_u32_e32 v2, 0x4000, v2
	ds_read_b64_tr_b16 v[150:151], v2 offset:0
	ds_read_b64_tr_b16 v[152:153], v2 offset:0x800
	ds_read_b64_tr_b16 v[154:155], v2 offset:0x1000
	ds_read_b64_tr_b16 v[156:157], v2 offset:0x1800
	ds_read_b64_tr_b16 v[158:159], v2 offset:0x2000
	ds_read_b64_tr_b16 v[160:161], v2 offset:0x2800
	v_mfma_f32_32x32x16_bf16 v[82:97], v[170:173], v[8:11], v[82:97]
	ds_read_b64_tr_b16 v[162:163], v2 offset:0x3000
	ds_read_b64_tr_b16 v[164:165], v2 offset:0x3800
	ds_read_b64_tr_b16 v[166:167], v2 offset:0x200
	ds_read_b64_tr_b16 v[168:169], v2 offset:0xa00
	ds_read_b64_tr_b16 v[170:171], v2 offset:0x1200
	ds_read_b64_tr_b16 v[172:173], v2 offset:0x1a00
	v_mfma_f32_32x32x16_bf16 v[82:97], v[174:177], v[146:149], v[82:97]
	ds_read_b64_tr_b16 v[174:175], v2 offset:0x2200
	ds_read_b64_tr_b16 v[176:177], v2 offset:0x2a00
	ds_read_b64_tr_b16 v[234:235], v2 offset:0x3200
	ds_read_b64_tr_b16 v[236:237], v2 offset:0x3a00
	s_waitcnt lgkmcnt(8)
	v_mfma_f32_32x32x16_bf16 v[82:97], v[230:233], v[12:15], v[82:97]
	v_mfma_f32_32x32x16_bf16 v[66:81], v[150:153], v[4:7], v[66:81]
	v_mfma_f32_32x32x16_bf16 v[66:81], v[154:157], v[8:11], v[66:81]
	v_mfma_f32_32x32x16_bf16 v[66:81], v[158:161], v[146:149], v[66:81]
	v_mfma_f32_32x32x16_bf16 v[66:81], v[162:165], v[12:15], v[66:81]
	ds_read_b64_tr_b16 v[150:151], v2 offset:0x400
	ds_read_b64_tr_b16 v[152:153], v2 offset:0xc00
	ds_read_b64_tr_b16 v[154:155], v2 offset:0x1400
	ds_read_b64_tr_b16 v[156:157], v2 offset:0x1c00
	ds_read_b64_tr_b16 v[158:159], v2 offset:0x2400
	ds_read_b64_tr_b16 v[160:161], v2 offset:0x2c00
	ds_read_b64_tr_b16 v[162:163], v2 offset:0x3400
	ds_read_b64_tr_b16 v[164:165], v2 offset:0x3c00
	s_waitcnt lgkmcnt(8)
	v_mfma_f32_32x32x16_bf16 v[50:65], v[166:169], v[4:7], v[50:65]
	v_mfma_f32_32x32x16_bf16 v[50:65], v[170:173], v[8:11], v[50:65]
	v_mfma_f32_32x32x16_bf16 v[50:65], v[174:177], v[146:149], v[50:65]
	v_mfma_f32_32x32x16_bf16 v[50:65], v[234:237], v[12:15], v[50:65]
	ds_read_b64_tr_b16 v[166:167], v2 offset:0x600
	ds_read_b64_tr_b16 v[168:169], v2 offset:0xe00
	ds_read_b64_tr_b16 v[170:171], v2 offset:0x1600
	ds_read_b64_tr_b16 v[172:173], v2 offset:0x1e00
	ds_read_b64_tr_b16 v[174:175], v2 offset:0x2600
	ds_read_b64_tr_b16 v[176:177], v2 offset:0x2e00
	ds_read_b64_tr_b16 v[230:231], v2 offset:0x3600
	ds_read_b64_tr_b16 v[232:233], v2 offset:0x3e00
	s_waitcnt lgkmcnt(8)
	v_mfma_f32_32x32x16_bf16 v[34:49], v[150:153], v[4:7], v[34:49]
	v_mfma_f32_32x32x16_bf16 v[34:49], v[154:157], v[8:11], v[34:49]
	v_mfma_f32_32x32x16_bf16 v[34:49], v[158:161], v[146:149], v[34:49]
	v_mfma_f32_32x32x16_bf16 v[34:49], v[162:165], v[12:15], v[34:49]
	s_waitcnt lgkmcnt(0)
	v_mfma_f32_32x32x16_bf16 v[18:33], v[166:169], v[4:7], v[18:33]
	s_add_i32 s6, s6, 64
	s_addk_i32 s76, 0x4000
	v_subrev_u32_e32 v227, 64, v227
	s_cmp_eq_u32 s75, s78
	v_mfma_f32_32x32x16_bf16 v[18:33], v[170:173], v[8:11], v[18:33]
	v_mfma_f32_32x32x16_bf16 v[18:33], v[174:177], v[146:149], v[18:33]
	v_mfma_f32_32x32x16_bf16 v[18:33], v[230:233], v[12:15], v[18:33]
	s_cbranch_scc1 .LBB0_357
	s_mov_b32 s80, s78
	v_mov_b32_e32 v229, v16
	s_mov_b32 s79, s77
	s_branch .LBB0_341
